# cross-attention core: 16 dwordx2 output stores paired via v_permlane16_swap into 8 dwordx4
# speedup vs baseline: 1.0111x; 1.0053x over previous
.LBB0_229:
	s_waitcnt lgkmcnt(0)
	s_barrier
	s_waitcnt vmcnt(0)
	ds_write_b128 v176, v[36:39]
	ds_write_b128 v177, v[40:43] offset:16384
	ds_write_b128 v178, v[52:55]
	ds_write_b128 v179, v[56:59] offset:16384
	ds_write_b128 v175, v[76:79]
	ds_write_b128 v174, v[68:71] offset:16384
	ds_write_b128 v173, v[88:91]
	ds_write_b128 v172, v[84:87] offset:16384
	v_lshl_add_u64 v[68:69], s[14:15], 0, v[132:133]
	v_add_co_u32_e32 v68, vcc, s38, v68
	v_lshl_add_u64 v[70:71], s[14:15], 0, v[138:139]
	s_nop 0
	v_addc_co_u32_e32 v69, vcc, 0, v69, vcc
	v_add_co_u32_e32 v70, vcc, s39, v70
	v_lshl_add_u64 v[76:77], s[14:15], 0, v[130:131]
	s_nop 0
	v_addc_co_u32_e32 v71, vcc, 0, v71, vcc
	v_add_co_u32_e32 v84, vcc, s38, v76
	v_lshl_add_u64 v[78:79], s[14:15], 0, v[136:137]
	s_nop 0
	v_addc_co_u32_e32 v85, vcc, 0, v77, vcc
	v_add_co_u32_e32 v86, vcc, s39, v78
	v_lshl_add_u64 v[36:37], s[14:15], 0, v[154:155]
	v_lshl_add_u64 v[40:41], s[14:15], 0, v[142:143]
	v_lshl_add_u64 v[52:53], s[14:15], 0, v[134:135]
	v_lshl_add_u64 v[56:57], s[14:15], 0, v[140:141]
	v_addc_co_u32_e32 v87, vcc, 0, v79, vcc
	s_waitcnt lgkmcnt(0)
	s_barrier
	flat_load_dwordx4 v[36:39], v[36:37]
	s_nop 0
	flat_load_dwordx4 v[40:43], v[40:41]
	s_nop 0
	flat_load_dwordx4 v[52:55], v[52:53]
	s_nop 0
	flat_load_dwordx4 v[56:59], v[56:57]
	s_nop 0
	flat_load_dwordx4 v[76:79], v[68:69]
	s_nop 0
	flat_load_dwordx4 v[68:71], v[70:71] offset:64
	s_nop 0
	flat_load_dwordx4 v[88:91], v[84:85]
	s_nop 0
	flat_load_dwordx4 v[84:87], v[86:87] offset:64
	v_mov_b32_e32 v144, v170
	v_mov_b32_e32 v220, v161
	ds_read_b128 v[146:149], v171
	ds_read_b128 v[180:183], v171 offset:8192
	s_waitcnt lgkmcnt(0)
	v_mfma_f32_16x16x32_bf16 v[180:183], v[180:183], v[28:31], 0
	v_mfma_f32_16x16x32_bf16 v[146:149], v[146:149], v[28:31], 0
	ds_read_b128 v[184:187], v169
	ds_read_b128 v[206:209], v169 offset:8192
	s_waitcnt lgkmcnt(0)
	v_mfma_f32_16x16x32_bf16 v[180:183], v[206:209], v[24:27], v[180:183]
	v_mfma_f32_16x16x32_bf16 v[146:149], v[184:187], v[24:27], v[146:149]
	ds_read_b128 v[184:187], v168
	ds_read_b128 v[206:209], v168 offset:8192
	s_waitcnt lgkmcnt(0)
	v_mfma_f32_16x16x32_bf16 v[180:183], v[206:209], v[20:23], v[180:183]
	v_mfma_f32_16x16x32_bf16 v[146:149], v[184:187], v[20:23], v[146:149]
	ds_read_b128 v[184:187], v167
	ds_read_b128 v[206:209], v167 offset:8192
	s_waitcnt lgkmcnt(0)
	v_mfma_f32_16x16x32_bf16 v[180:183], v[206:209], v[16:19], v[180:183]
	v_mfma_f32_16x16x32_bf16 v[146:149], v[184:187], v[16:19], v[146:149]
	ds_read_b128 v[184:187], v166
	ds_read_b128 v[206:209], v166 offset:8192
	s_waitcnt lgkmcnt(0)
	v_mfma_f32_16x16x32_bf16 v[180:183], v[206:209], v[12:15], v[180:183]
	v_mfma_f32_16x16x32_bf16 v[146:149], v[184:187], v[12:15], v[146:149]
	ds_read_b128 v[184:187], v165
	ds_read_b128 v[206:209], v165 offset:8192
	s_waitcnt lgkmcnt(0)
	v_mfma_f32_16x16x32_bf16 v[180:183], v[206:209], v[8:11], v[180:183]
	v_mfma_f32_16x16x32_bf16 v[146:149], v[184:187], v[8:11], v[146:149]
	ds_read_b128 v[184:187], v163
	ds_read_b128 v[206:209], v163 offset:8192
	s_waitcnt lgkmcnt(0)
	v_mfma_f32_16x16x32_bf16 v[180:183], v[206:209], v[4:7], v[180:183]
	v_mfma_f32_16x16x32_bf16 v[146:149], v[184:187], v[4:7], v[146:149]
	ds_read_b128 v[184:187], v162
	ds_read_b128 v[206:209], v162 offset:8192
	s_waitcnt lgkmcnt(0)
	v_mfma_f32_16x16x32_bf16 v[180:183], v[206:209], v[0:3], v[180:183]
	v_mfma_f32_16x16x32_bf16 v[146:149], v[184:187], v[0:3], v[146:149]
	s_nop 7
	v_max_f32_e32 v161, v149, v149
	v_max_f32_e32 v170, v148, v148
	v_max_f32_e32 v161, v170, v161
	v_max_f32_e32 v170, v183, v183
	v_max_f32_e32 v184, v182, v182
	v_max_f32_e32 v170, v184, v170
	v_max3_f32 v161, v146, v147, v161
	v_max3_f32 v170, v180, v181, v170
	v_max3_f32 v161, v161, s42, v170
	ds_bpermute_b32 v170, v156, v161
	s_waitcnt lgkmcnt(0)
	v_max_f32_e32 v170, v170, v170
	v_max_f32_e32 v161, v161, v170
	ds_bpermute_b32 v170, v157, v161
	s_waitcnt lgkmcnt(0)
	v_max_f32_e32 v170, v170, v170
	v_max_f32_e32 v161, v161, v170
	v_mul_f32_e32 v161, 0x3db8aa3b, v161
	v_max_f32_e32 v170, v144, v144
	v_max_f32_e32 v170, v170, v161
	v_fma_f32 v146, v146, s82, -v170
	v_exp_f32_e32 v146, v146
	v_fma_f32 v147, v147, s82, -v170
	v_exp_f32_e32 v147, v147
	v_fma_f32 v148, v148, s82, -v170
	v_exp_f32_e32 v148, v148
	v_fma_f32 v149, v149, s82, -v170
	v_exp_f32_e32 v149, v149
	v_add_f32_e32 v161, 0, v146
	v_cvt_pk_bf16_f32 v146, v146, v147
	v_add_f32_e32 v161, v147, v161
	v_cvt_pk_bf16_f32 v147, v148, v149
	ds_write_b64 v160, v[146:147] offset:32768
	v_fma_f32 v146, v180, s82, -v170
	v_add_f32_e32 v161, v148, v161
	v_exp_f32_e32 v148, v146
	v_fma_f32 v146, v181, s82, -v170
	v_add_f32_e32 v161, v149, v161
	v_exp_f32_e32 v149, v146
	v_fma_f32 v146, v182, s82, -v170
	v_exp_f32_e32 v180, v146
	v_fma_f32 v146, v183, s82, -v170
	v_exp_f32_e32 v181, v146
	v_cvt_pk_bf16_f32 v146, v148, v149
	v_cvt_pk_bf16_f32 v147, v180, v181
	ds_write_b64 v159, v[146:147] offset:32768
	v_add_f32_e32 v146, v148, v161
	v_add_f32_e32 v146, v149, v146
	v_add_f32_e32 v146, v180, v146
	v_add_f32_e32 v161, v181, v146
	v_add_u32_e32 v181, v158, v164
	v_add_u32_e32 v180, s60, v164
	ds_read_b128 v[146:149], v181 offset:32768
	ds_read_b128 v[182:185], v180 offset:16384
	ds_read_b128 v[186:189], v180 offset:17408
	ds_read_b128 v[206:209], v180 offset:18432
	ds_read_b128 v[216:219], v180 offset:19456
	v_sub_f32_e32 v144, v144, v170
	v_exp_f32_e32 v144, v144
	s_nop 0
	v_pk_mul_f32 v[126:127], v[126:127], v[144:145] op_sel_hi:[1,0]
	v_pk_mul_f32 v[124:125], v[124:125], v[144:145] op_sel_hi:[1,0]
	v_pk_mul_f32 v[122:123], v[122:123], v[144:145] op_sel_hi:[1,0]
	v_pk_mul_f32 v[120:121], v[120:121], v[144:145] op_sel_hi:[1,0]
	v_pk_mul_f32 v[118:119], v[118:119], v[144:145] op_sel_hi:[1,0]
	v_pk_mul_f32 v[116:117], v[116:117], v[144:145] op_sel_hi:[1,0]
	v_pk_mul_f32 v[114:115], v[114:115], v[144:145] op_sel_hi:[1,0]
	v_pk_mul_f32 v[112:113], v[112:113], v[144:145] op_sel_hi:[1,0]
	v_pk_mul_f32 v[110:111], v[110:111], v[144:145] op_sel_hi:[1,0]
	v_pk_mul_f32 v[108:109], v[108:109], v[144:145] op_sel_hi:[1,0]
	v_pk_mul_f32 v[106:107], v[106:107], v[144:145] op_sel_hi:[1,0]
	v_pk_mul_f32 v[104:105], v[104:105], v[144:145] op_sel_hi:[1,0]
	v_pk_mul_f32 v[102:103], v[102:103], v[144:145] op_sel_hi:[1,0]
	v_pk_mul_f32 v[100:101], v[100:101], v[144:145] op_sel_hi:[1,0]
	v_pk_mul_f32 v[98:99], v[98:99], v[144:145] op_sel_hi:[1,0]
	v_pk_mul_f32 v[96:97], v[96:97], v[144:145] op_sel_hi:[1,0]
	v_pk_mul_f32 v[94:95], v[94:95], v[144:145] op_sel_hi:[1,0]
	v_pk_mul_f32 v[92:93], v[92:93], v[144:145] op_sel_hi:[1,0]
	v_pk_mul_f32 v[82:83], v[82:83], v[144:145] op_sel_hi:[1,0]
	v_pk_mul_f32 v[80:81], v[80:81], v[144:145] op_sel_hi:[1,0]
	v_pk_mul_f32 v[74:75], v[74:75], v[144:145] op_sel_hi:[1,0]
	v_pk_mul_f32 v[72:73], v[72:73], v[144:145] op_sel_hi:[1,0]
	v_pk_mul_f32 v[66:67], v[66:67], v[144:145] op_sel_hi:[1,0]
	v_pk_mul_f32 v[64:65], v[64:65], v[144:145] op_sel_hi:[1,0]
	v_pk_mul_f32 v[62:63], v[62:63], v[144:145] op_sel_hi:[1,0]
	v_pk_mul_f32 v[60:61], v[60:61], v[144:145] op_sel_hi:[1,0]
	v_pk_mul_f32 v[50:51], v[50:51], v[144:145] op_sel_hi:[1,0]
	v_pk_mul_f32 v[48:49], v[48:49], v[144:145] op_sel_hi:[1,0]
	v_pk_mul_f32 v[46:47], v[46:47], v[144:145] op_sel_hi:[1,0]
	v_pk_mul_f32 v[44:45], v[44:45], v[144:145] op_sel_hi:[1,0]
	v_pk_mul_f32 v[34:35], v[34:35], v[144:145] op_sel_hi:[1,0]
	v_pk_mul_f32 v[32:33], v[32:33], v[144:145] op_sel_hi:[1,0]
	s_waitcnt lgkmcnt(0)
	v_mfma_f32_16x16x32_bf16 v[124:127], v[182:185], v[146:149], v[124:127]
	v_mfma_f32_16x16x32_bf16 v[120:123], v[186:189], v[146:149], v[120:123]
	v_mfma_f32_16x16x32_bf16 v[116:119], v[206:209], v[146:149], v[116:119]
	v_mfma_f32_16x16x32_bf16 v[112:115], v[216:219], v[146:149], v[112:115]
	ds_read_b128 v[182:185], v180 offset:20480
	ds_read_b128 v[186:189], v180 offset:21504
	ds_read_b128 v[206:209], v180 offset:22528
	ds_read_b128 v[216:219], v180 offset:23552
	s_waitcnt lgkmcnt(0)
	v_mfma_f32_16x16x32_bf16 v[108:111], v[182:185], v[146:149], v[108:111]
	v_mfma_f32_16x16x32_bf16 v[104:107], v[186:189], v[146:149], v[104:107]
	v_mfma_f32_16x16x32_bf16 v[100:103], v[206:209], v[146:149], v[100:103]
	v_mfma_f32_16x16x32_bf16 v[96:99], v[216:219], v[146:149], v[96:99]
	ds_read_b128 v[182:185], v180 offset:24576
	ds_read_b128 v[186:189], v180 offset:25600
	ds_read_b128 v[206:209], v180 offset:26624
	ds_read_b128 v[216:219], v180 offset:27648
	s_waitcnt lgkmcnt(0)
	v_mfma_f32_16x16x32_bf16 v[92:95], v[182:185], v[146:149], v[92:95]
	v_mfma_f32_16x16x32_bf16 v[80:83], v[186:189], v[146:149], v[80:83]
	v_mfma_f32_16x16x32_bf16 v[72:75], v[206:209], v[146:149], v[72:75]
	v_mfma_f32_16x16x32_bf16 v[64:67], v[216:219], v[146:149], v[64:67]
	ds_read_b128 v[182:185], v180 offset:28672
	ds_read_b128 v[186:189], v180 offset:29696
	ds_read_b128 v[206:209], v180 offset:30720
	ds_read_b128 v[216:219], v180 offset:31744
	s_waitcnt lgkmcnt(0)
	v_mfma_f32_16x16x32_bf16 v[60:63], v[182:185], v[146:149], v[60:63]
	v_mfma_f32_16x16x32_bf16 v[48:51], v[186:189], v[146:149], v[48:51]
	v_mfma_f32_16x16x32_bf16 v[44:47], v[206:209], v[146:149], v[44:47]
	v_mfma_f32_16x16x32_bf16 v[32:35], v[216:219], v[146:149], v[32:35]
	s_add_i32 s0, s0, -1
	v_fmac_f32_e32 v161, v220, v144
	v_lshl_add_u64 v[130:131], v[130:131], 0, s[40:41]
	v_lshl_add_u64 v[132:133], v[132:133], 0, s[40:41]
	v_lshl_add_u64 v[134:135], v[134:135], 0, s[40:41]
	v_lshl_add_u64 v[136:137], v[136:137], 0, 64
	v_lshl_add_u64 v[138:139], v[138:139], 0, 64
	v_lshl_add_u64 v[140:141], v[140:141], 0, 64
	v_lshl_add_u64 v[142:143], v[142:143], 0, 64
	s_cmp_lg_u32 s0, 0
	v_lshl_add_u64 v[154:155], v[154:155], 0, s[40:41]
	s_cbranch_scc1 .LBB0_229
	s_lshl_b64 s[6:7], s[6:7], 1
	s_add_u32 s0, s30, s6
	s_addc_u32 s7, s31, s7
	s_lshl_b32 s6, s37, 1
	s_add_u32 s6, s0, s6
	s_addc_u32 s7, s7, 0
	s_barrier
	s_waitcnt vmcnt(0)
	ds_write_b128 v176, v[36:39]
	ds_write_b128 v177, v[40:43] offset:16384
	ds_write_b128 v178, v[52:55]
	ds_write_b128 v179, v[56:59] offset:16384
	ds_write_b128 v175, v[76:79]
	ds_write_b128 v174, v[68:71] offset:16384
	ds_write_b128 v173, v[88:91]
	ds_write_b128 v172, v[84:87] offset:16384
	s_waitcnt lgkmcnt(0)
	s_barrier
	ds_read_b128 v[36:39], v171
	ds_read_b128 v[40:43], v171 offset:8192
	s_waitcnt lgkmcnt(1)
	v_mfma_f32_16x16x32_bf16 v[36:39], v[36:39], v[28:31], 0
	s_waitcnt lgkmcnt(0)
	v_mfma_f32_16x16x32_bf16 v[28:31], v[40:43], v[28:31], 0
	ds_read_b128 v[40:43], v169
	ds_read_b128 v[52:55], v169 offset:8192
	s_waitcnt lgkmcnt(1)
	v_mfma_f32_16x16x32_bf16 v[36:39], v[40:43], v[24:27], v[36:39]
	s_waitcnt lgkmcnt(0)
	v_mfma_f32_16x16x32_bf16 v[24:27], v[52:55], v[24:27], v[28:31]
	s_nop 2
	ds_read_b128 v[28:31], v168
	ds_read_b128 v[40:43], v168 offset:8192
	s_waitcnt lgkmcnt(1)
	v_mfma_f32_16x16x32_bf16 v[28:31], v[28:31], v[20:23], v[36:39]
	s_waitcnt lgkmcnt(0)
	v_mfma_f32_16x16x32_bf16 v[20:23], v[40:43], v[20:23], v[24:27]
	s_nop 2
	ds_read_b128 v[24:27], v167
	ds_read_b128 v[36:39], v167 offset:8192
	s_waitcnt lgkmcnt(1)
	v_mfma_f32_16x16x32_bf16 v[24:27], v[24:27], v[16:19], v[28:31]
	s_waitcnt lgkmcnt(0)
	v_mfma_f32_16x16x32_bf16 v[16:19], v[36:39], v[16:19], v[20:23]
	s_nop 2
	ds_read_b128 v[20:23], v166
	ds_read_b128 v[28:31], v166 offset:8192
	s_waitcnt lgkmcnt(1)
	v_mfma_f32_16x16x32_bf16 v[20:23], v[20:23], v[12:15], v[24:27]
	s_waitcnt lgkmcnt(0)
	v_mfma_f32_16x16x32_bf16 v[12:15], v[28:31], v[12:15], v[16:19]
	s_nop 2
	ds_read_b128 v[16:19], v165
	ds_read_b128 v[24:27], v165 offset:8192
	s_waitcnt lgkmcnt(1)
	v_mfma_f32_16x16x32_bf16 v[16:19], v[16:19], v[8:11], v[20:23]
	s_waitcnt lgkmcnt(0)
	v_mfma_f32_16x16x32_bf16 v[8:11], v[24:27], v[8:11], v[12:15]
	s_nop 2
	ds_read_b128 v[12:15], v163
	ds_read_b128 v[20:23], v163 offset:8192
	s_waitcnt lgkmcnt(1)
	v_mfma_f32_16x16x32_bf16 v[12:15], v[12:15], v[4:7], v[16:19]
	s_waitcnt lgkmcnt(0)
	v_mfma_f32_16x16x32_bf16 v[4:7], v[20:23], v[4:7], v[8:11]
	s_nop 2
	ds_read_b128 v[8:11], v162
	ds_read_b128 v[16:19], v162 offset:8192
	s_waitcnt lgkmcnt(1)
	v_mfma_f32_16x16x32_bf16 v[8:11], v[8:11], v[0:3], v[12:15]
	s_waitcnt lgkmcnt(0)
	v_mfma_f32_16x16x32_bf16 v[2:5], v[16:19], v[0:3], v[4:7]
	s_nop 5
	v_max_f32_e32 v0, v11, v11
	v_max_f32_e32 v1, v10, v10
	v_max_f32_e32 v0, v1, v0
	v_max_f32_e32 v1, v5, v5
	v_max_f32_e32 v6, v4, v4
	v_max_f32_e32 v1, v6, v1
	v_max3_f32 v0, v8, v9, v0
	v_max3_f32 v1, v2, v3, v1
	v_max3_f32 v0, v0, s42, v1
	ds_bpermute_b32 v1, v156, v0
	s_waitcnt lgkmcnt(0)
	v_max_f32_e32 v1, v1, v1
	v_max_f32_e32 v0, v0, v1
	ds_bpermute_b32 v1, v157, v0
	s_waitcnt lgkmcnt(0)
	v_max_f32_e32 v1, v1, v1
	v_max_f32_e32 v0, v0, v1
	v_mul_f32_e32 v0, 0x3db8aa3b, v0
	v_max_f32_e32 v1, v170, v170
	v_max_f32_e32 v1, v1, v0
	v_fma_f32 v6, v8, s82, -v1
	v_exp_f32_e32 v6, v6
	v_fma_f32 v8, v9, s82, -v1
	v_exp_f32_e32 v8, v8
	v_fma_f32 v9, v10, s82, -v1
	v_exp_f32_e32 v9, v9
	v_fma_f32 v10, v11, s82, -v1
	v_exp_f32_e32 v10, v10
	v_fma_f32 v2, v2, s82, -v1
	v_add_f32_e32 v7, 0, v6
	v_exp_f32_e32 v31, v2
	v_fma_f32 v2, v3, s82, -v1
	v_sub_f32_e32 v0, v170, v1
	v_add_f32_e32 v7, v8, v7
	v_exp_f32_e32 v68, v2
	v_fma_f32 v2, v4, s82, -v1
	v_fma_f32 v1, v5, s82, -v1
	v_exp_f32_e32 v0, v0
	v_add_f32_e32 v7, v9, v7
	v_exp_f32_e32 v69, v2
	v_exp_f32_e32 v1, v1
	v_add_f32_e32 v30, v10, v7
	v_cvt_pk_bf16_f32 v6, v6, v8
	v_cvt_pk_bf16_f32 v7, v9, v10
	ds_write_b64 v160, v[6:7] offset:32768
	v_cvt_pk_bf16_f32 v2, v31, v68
	v_cvt_pk_bf16_f32 v3, v69, v1
	ds_write_b64 v159, v[2:3] offset:32768
	v_add_f32_e32 v30, v31, v30
	v_add_f32_e32 v30, v68, v30
	v_pk_mul_f32 v[54:55], v[82:83], v[0:1] op_sel_hi:[1,0]
	v_pk_mul_f32 v[52:53], v[80:81], v[0:1] op_sel_hi:[1,0]
	v_pk_mul_f32 v[58:59], v[74:75], v[0:1] op_sel_hi:[1,0]
	v_pk_mul_f32 v[56:57], v[72:73], v[0:1] op_sel_hi:[1,0]
	v_add_f32_e32 v30, v69, v30
	ds_read_b128 v[68:71], v181 offset:32768
	ds_read_b128 v[72:75], v180 offset:16384
	ds_read_b128 v[76:79], v180 offset:17408
	ds_read_b128 v[80:83], v180 offset:18432
	ds_read_b128 v[84:87], v180 offset:19456
	v_pk_mul_f32 v[4:5], v[126:127], v[0:1] op_sel_hi:[1,0]
	v_pk_mul_f32 v[2:3], v[124:125], v[0:1] op_sel_hi:[1,0]
	v_pk_mul_f32 v[8:9], v[122:123], v[0:1] op_sel_hi:[1,0]
	v_pk_mul_f32 v[6:7], v[120:121], v[0:1] op_sel_hi:[1,0]
	v_pk_mul_f32 v[12:13], v[118:119], v[0:1] op_sel_hi:[1,0]
	v_pk_mul_f32 v[10:11], v[116:117], v[0:1] op_sel_hi:[1,0]
	v_pk_mul_f32 v[16:17], v[114:115], v[0:1] op_sel_hi:[1,0]
	v_pk_mul_f32 v[14:15], v[112:113], v[0:1] op_sel_hi:[1,0]
	v_pk_mul_f32 v[20:21], v[110:111], v[0:1] op_sel_hi:[1,0]
	v_pk_mul_f32 v[18:19], v[108:109], v[0:1] op_sel_hi:[1,0]
	v_pk_mul_f32 v[24:25], v[106:107], v[0:1] op_sel_hi:[1,0]
	v_pk_mul_f32 v[22:23], v[104:105], v[0:1] op_sel_hi:[1,0]
	v_pk_mul_f32 v[28:29], v[102:103], v[0:1] op_sel_hi:[1,0]
	v_pk_mul_f32 v[26:27], v[100:101], v[0:1] op_sel_hi:[1,0]
	v_pk_mul_f32 v[38:39], v[98:99], v[0:1] op_sel_hi:[1,0]
	v_pk_mul_f32 v[36:37], v[96:97], v[0:1] op_sel_hi:[1,0]
	v_pk_mul_f32 v[42:43], v[94:95], v[0:1] op_sel_hi:[1,0]
	v_pk_mul_f32 v[40:41], v[92:93], v[0:1] op_sel_hi:[1,0]
	v_pk_mul_f32 v[66:67], v[66:67], v[0:1] op_sel_hi:[1,0]
	v_pk_mul_f32 v[64:65], v[64:65], v[0:1] op_sel_hi:[1,0]
	v_pk_mul_f32 v[62:63], v[62:63], v[0:1] op_sel_hi:[1,0]
	v_pk_mul_f32 v[60:61], v[60:61], v[0:1] op_sel_hi:[1,0]
	v_pk_mul_f32 v[50:51], v[50:51], v[0:1] op_sel_hi:[1,0]
	v_pk_mul_f32 v[48:49], v[48:49], v[0:1] op_sel_hi:[1,0]
	v_pk_mul_f32 v[46:47], v[46:47], v[0:1] op_sel_hi:[1,0]
	v_pk_mul_f32 v[44:45], v[44:45], v[0:1] op_sel_hi:[1,0]
	v_pk_mul_f32 v[34:35], v[34:35], v[0:1] op_sel_hi:[1,0]
	v_pk_mul_f32 v[32:33], v[32:33], v[0:1] op_sel_hi:[1,0]
	v_add_f32_e32 v1, v1, v30
	s_waitcnt lgkmcnt(3)
	v_mfma_f32_16x16x32_bf16 v[2:5], v[72:75], v[68:71], v[2:5]
	s_waitcnt lgkmcnt(2)
	v_mfma_f32_16x16x32_bf16 v[6:9], v[76:79], v[68:71], v[6:9]
	s_waitcnt lgkmcnt(1)
	v_mfma_f32_16x16x32_bf16 v[10:13], v[80:83], v[68:71], v[10:13]
	s_waitcnt lgkmcnt(0)
	v_mfma_f32_16x16x32_bf16 v[14:17], v[84:87], v[68:71], v[14:17]
	ds_read_b128 v[72:75], v180 offset:20480
	ds_read_b128 v[76:79], v180 offset:21504
	ds_read_b128 v[80:83], v180 offset:22528
	ds_read_b128 v[84:87], v180 offset:23552
	s_waitcnt lgkmcnt(3)
	v_mfma_f32_16x16x32_bf16 v[18:21], v[72:75], v[68:71], v[18:21]
	s_waitcnt lgkmcnt(2)
	v_mfma_f32_16x16x32_bf16 v[22:25], v[76:79], v[68:71], v[22:25]
	s_waitcnt lgkmcnt(1)
	v_mfma_f32_16x16x32_bf16 v[26:29], v[80:83], v[68:71], v[26:29]
	s_waitcnt lgkmcnt(0)
	v_mfma_f32_16x16x32_bf16 v[36:39], v[84:87], v[68:71], v[36:39]
	ds_read_b128 v[72:75], v180 offset:24576
	ds_read_b128 v[76:79], v180 offset:25600
	ds_read_b128 v[80:83], v180 offset:26624
	ds_read_b128 v[84:87], v180 offset:27648
	s_waitcnt lgkmcnt(3)
	v_mfma_f32_16x16x32_bf16 v[40:43], v[72:75], v[68:71], v[40:43]
	s_waitcnt lgkmcnt(2)
	v_mfma_f32_16x16x32_bf16 v[52:55], v[76:79], v[68:71], v[52:55]
	s_waitcnt lgkmcnt(1)
	v_mfma_f32_16x16x32_bf16 v[56:59], v[80:83], v[68:71], v[56:59]
	s_waitcnt lgkmcnt(0)
	v_mfma_f32_16x16x32_bf16 v[64:67], v[84:87], v[68:71], v[64:67]
	ds_read_b128 v[72:75], v180 offset:28672
	ds_read_b128 v[76:79], v180 offset:29696
	ds_read_b128 v[80:83], v180 offset:30720
	ds_read_b128 v[84:87], v180 offset:31744
	s_waitcnt lgkmcnt(3)
	v_mfma_f32_16x16x32_bf16 v[60:63], v[72:75], v[68:71], v[60:63]
	s_waitcnt lgkmcnt(2)
	v_mfma_f32_16x16x32_bf16 v[48:51], v[76:79], v[68:71], v[48:51]
	s_waitcnt lgkmcnt(1)
	v_mfma_f32_16x16x32_bf16 v[44:47], v[80:83], v[68:71], v[44:47]
	s_waitcnt lgkmcnt(0)
	v_mfma_f32_16x16x32_bf16 v[30:33], v[84:87], v[68:71], v[32:35]
	v_fmac_f32_e32 v1, v161, v0
	ds_bpermute_b32 v0, v156, v1
	v_lshlrev_b32_e32 v144, 3, v151
	v_readlane_b32 s0, v255, 15
	s_add_i32 s34, s34, s0
	v_readlane_b32 s0, v255, 17
	s_waitcnt lgkmcnt(0)
	v_add_f32_e32 v34, v1, v0
	ds_bpermute_b32 v35, v157, v34
	v_lshl_add_u64 v[0:1], s[6:7], 0, v[128:129]
	v_lshl_add_u64 v[0:1], v[0:1], 0, v[144:145]
	s_add_i32 s36, s36, s70
	s_add_i32 s35, s35, s0
	s_waitcnt lgkmcnt(0)
	v_add_f32_e32 v34, v34, v35
	v_div_scale_f32 v35, s[6:7], v34, v34, 1.0
	v_rcp_f32_e32 v68, v35
	v_div_scale_f32 v69, vcc, 1.0, v34, 1.0
	s_cmpk_gt_i32 s36, 0x3ff
	v_fma_f32 v70, -v35, v68, 1.0
	v_fmac_f32_e32 v68, v70, v68
	v_mul_f32_e32 v70, v69, v68
	v_fma_f32 v71, -v35, v70, v69
	v_fmac_f32_e32 v70, v71, v68
	v_fma_f32 v35, -v35, v70, v69
	v_div_fmas_f32 v35, v35, v68, v70
	v_div_fixup_f32 v34, v35, v34, 1.0
	v_pk_mul_f32 v[2:3], v[2:3], v[34:35] op_sel_hi:[1,0]
	v_pk_mul_f32 v[4:5], v[4:5], v[34:35] op_sel_hi:[1,0]
	v_cvt_pk_bf16_f32 v2, v2, v3
	v_pk_mul_f32 v[8:9], v[8:9], v[34:35] op_sel_hi:[1,0]
	v_cvt_pk_bf16_f32 v3, v4, v5
	v_pk_mul_f32 v[6:7], v[6:7], v[34:35] op_sel_hi:[1,0]
	v_and_b32_e32 v242, 16, v190
	v_mul_u32_u24_e32 v242, 3, v242
	v_lshrrev_b32_e32 v242, 1, v242
	v_mov_b32_e32 v243, 0
	v_lshl_add_u64 v[240:241], v[0:1], 0, v[242:243]
	v_mov_b32_e32 v248, v2
	v_mov_b32_e32 v249, v3
	v_cvt_pk_bf16_f32 v2, v6, v7
	v_cvt_pk_bf16_f32 v3, v8, v9
	v_pk_mul_f32 v[4:5], v[10:11], v[34:35] op_sel_hi:[1,0]
	v_mov_b32_e32 v250, v2
	v_mov_b32_e32 v251, v3
	s_nop 1
	v_permlane16_swap_b32 v248, v250
	v_permlane16_swap_b32 v249, v251
	flat_store_dwordx4 v[240:241], v[248:251]
	v_pk_mul_f32 v[2:3], v[12:13], v[34:35] op_sel_hi:[1,0]
	v_cvt_pk_bf16_f32 v4, v4, v5
	s_nop 0
	v_cvt_pk_bf16_f32 v5, v2, v3
	v_mov_b32_e32 v248, v4
	v_mov_b32_e32 v249, v5
	v_pk_mul_f32 v[4:5], v[14:15], v[34:35] op_sel_hi:[1,0]
	v_pk_mul_f32 v[2:3], v[16:17], v[34:35] op_sel_hi:[1,0]
	v_cvt_pk_bf16_f32 v4, v4, v5
	s_nop 0
	v_cvt_pk_bf16_f32 v5, v2, v3
	v_mov_b32_e32 v250, v4
	v_mov_b32_e32 v251, v5
	s_nop 1
	v_permlane16_swap_b32 v248, v250
	v_permlane16_swap_b32 v249, v251
	flat_store_dwordx4 v[240:241], v[248:251] offset:64
	v_pk_mul_f32 v[4:5], v[18:19], v[34:35] op_sel_hi:[1,0]
	v_pk_mul_f32 v[2:3], v[20:21], v[34:35] op_sel_hi:[1,0]
	v_cvt_pk_bf16_f32 v4, v4, v5
	s_nop 0
	v_cvt_pk_bf16_f32 v5, v2, v3
	v_mov_b32_e32 v248, v4
	v_mov_b32_e32 v249, v5
	v_pk_mul_f32 v[4:5], v[22:23], v[34:35] op_sel_hi:[1,0]
	v_pk_mul_f32 v[2:3], v[24:25], v[34:35] op_sel_hi:[1,0]
	v_cvt_pk_bf16_f32 v4, v4, v5
	s_nop 0
	v_cvt_pk_bf16_f32 v5, v2, v3
	v_mov_b32_e32 v250, v4
	v_mov_b32_e32 v251, v5
	s_nop 1
	v_permlane16_swap_b32 v248, v250
	v_permlane16_swap_b32 v249, v251
	flat_store_dwordx4 v[240:241], v[248:251] offset:128
	v_pk_mul_f32 v[4:5], v[26:27], v[34:35] op_sel_hi:[1,0]
	v_pk_mul_f32 v[2:3], v[28:29], v[34:35] op_sel_hi:[1,0]
	v_cvt_pk_bf16_f32 v4, v4, v5
	s_nop 0
	v_cvt_pk_bf16_f32 v5, v2, v3
	v_mov_b32_e32 v248, v4
	v_mov_b32_e32 v249, v5
	v_pk_mul_f32 v[4:5], v[36:37], v[34:35] op_sel_hi:[1,0]
	v_pk_mul_f32 v[2:3], v[38:39], v[34:35] op_sel_hi:[1,0]
	v_cvt_pk_bf16_f32 v4, v4, v5
	s_nop 0
	v_cvt_pk_bf16_f32 v5, v2, v3
	v_mov_b32_e32 v250, v4
	v_mov_b32_e32 v251, v5
	s_nop 1
	v_permlane16_swap_b32 v248, v250
	v_permlane16_swap_b32 v249, v251
	flat_store_dwordx4 v[240:241], v[248:251] offset:192
	v_pk_mul_f32 v[4:5], v[40:41], v[34:35] op_sel_hi:[1,0]
	v_pk_mul_f32 v[2:3], v[42:43], v[34:35] op_sel_hi:[1,0]
	v_cvt_pk_bf16_f32 v4, v4, v5
	s_nop 0
	v_cvt_pk_bf16_f32 v5, v2, v3
	v_mov_b32_e32 v248, v4
	v_mov_b32_e32 v249, v5
	v_pk_mul_f32 v[4:5], v[52:53], v[34:35] op_sel_hi:[1,0]
	v_pk_mul_f32 v[2:3], v[54:55], v[34:35] op_sel_hi:[1,0]
	v_cvt_pk_bf16_f32 v4, v4, v5
	s_nop 0
	v_cvt_pk_bf16_f32 v5, v2, v3
	v_mov_b32_e32 v250, v4
	v_mov_b32_e32 v251, v5
	s_nop 1
	v_permlane16_swap_b32 v248, v250
	v_permlane16_swap_b32 v249, v251
	flat_store_dwordx4 v[240:241], v[248:251] offset:256
	v_pk_mul_f32 v[4:5], v[56:57], v[34:35] op_sel_hi:[1,0]
	v_pk_mul_f32 v[2:3], v[58:59], v[34:35] op_sel_hi:[1,0]
	v_cvt_pk_bf16_f32 v4, v4, v5
	s_nop 0
	v_cvt_pk_bf16_f32 v5, v2, v3
	v_mov_b32_e32 v248, v4
	v_mov_b32_e32 v249, v5
	v_pk_mul_f32 v[4:5], v[64:65], v[34:35] op_sel_hi:[1,0]
	v_pk_mul_f32 v[2:3], v[66:67], v[34:35] op_sel_hi:[1,0]
	v_cvt_pk_bf16_f32 v4, v4, v5
	s_nop 0
	v_cvt_pk_bf16_f32 v5, v2, v3
	v_mov_b32_e32 v250, v4
	v_mov_b32_e32 v251, v5
	s_nop 1
	v_permlane16_swap_b32 v248, v250
	v_permlane16_swap_b32 v249, v251
	flat_store_dwordx4 v[240:241], v[248:251] offset:320
	v_pk_mul_f32 v[4:5], v[60:61], v[34:35] op_sel_hi:[1,0]
	v_pk_mul_f32 v[2:3], v[62:63], v[34:35] op_sel_hi:[1,0]
	v_cvt_pk_bf16_f32 v4, v4, v5
	s_nop 0
	v_cvt_pk_bf16_f32 v5, v2, v3
	v_mov_b32_e32 v248, v4
	v_mov_b32_e32 v249, v5
	v_pk_mul_f32 v[4:5], v[48:49], v[34:35] op_sel_hi:[1,0]
	v_pk_mul_f32 v[2:3], v[50:51], v[34:35] op_sel_hi:[1,0]
	v_cvt_pk_bf16_f32 v4, v4, v5
	s_nop 0
	v_cvt_pk_bf16_f32 v5, v2, v3
	v_mov_b32_e32 v250, v4
	v_mov_b32_e32 v251, v5
	s_nop 1
	v_permlane16_swap_b32 v248, v250
	v_permlane16_swap_b32 v249, v251
	flat_store_dwordx4 v[240:241], v[248:251] offset:384
	v_pk_mul_f32 v[4:5], v[44:45], v[34:35] op_sel_hi:[1,0]
	v_pk_mul_f32 v[2:3], v[46:47], v[34:35] op_sel_hi:[1,0]
	v_cvt_pk_bf16_f32 v4, v4, v5
	s_nop 0
	v_cvt_pk_bf16_f32 v5, v2, v3
	v_mov_b32_e32 v248, v4
	v_mov_b32_e32 v249, v5
	v_pk_mul_f32 v[4:5], v[30:31], v[34:35] op_sel_hi:[1,0]
	v_pk_mul_f32 v[2:3], v[32:33], v[34:35] op_sel_hi:[1,0]
	v_cvt_pk_bf16_f32 v4, v4, v5
	s_nop 0
	v_cvt_pk_bf16_f32 v5, v2, v3
	v_mov_b32_e32 v250, v4
	v_mov_b32_e32 v251, v5
	s_nop 1
	v_permlane16_swap_b32 v248, v250
	v_permlane16_swap_b32 v249, v251
	flat_store_dwordx4 v[240:241], v[248:251] offset:448
	s_cbranch_scc0 .LBB0_228
